# grid barrier: agent-scope L1 invalidate issued on arrival so it overlaps the wait (one workgroup per CU reads nothing but barrier words in between)
# speedup vs baseline: 1.0045x; 1.0045x over previous
; __device__ __forceinline__ unsigned xb_ld(unsigned* p)              { return __hip_atomic_load(p, __ATOMIC_RELAXED, __HIP_MEMORY_SCOPE_AGENT); }
; __device__ __forceinline__ unsigned xb_add(unsigned* p, unsigned v) { return __hip_atomic_fetch_add(p, v, __ATOMIC_RELAXED, __HIP_MEMORY_SCOPE_AGENT); }
; #define XB_SPIN(cond, bar) do { unsigned _sp = 0; while (cond) { __builtin_amdgcn_s_sleep(1); \
;     if ((++_sp & 255u) == 0u) { if (xb_ld(&(bar)[XB_TMO])) break; if (_sp > XB_SPIN_CAP) { atomicAdd(&(bar)[XB_TMO], 1u); break; } } } } while (0)
; __device__ __forceinline__ void xcd_barrier(unsigned* bar, unsigned x, volatile LAS unsigned* st) {
;     ...
;         const unsigned old = xb_add(&bar[XB_XSUB(x)], 1u);
;         const unsigned gen = old / nloc;
;         if (old + 1u == (gen + 1u) * nloc) {
;             __builtin_amdgcn_fence(__ATOMIC_RELEASE, "agent");
;             asm volatile("s_waitcnt vmcnt(0)" ::: "memory");
;             const unsigned og = xb_add(&bar[XB_TOP], 1u);
;             const unsigned tg = og / nx;
;             if (og + 1u == (tg + 1u) * nx) xb_add(&bar[XB_TOPGEN], 1u);
;             else XB_SPIN(xb_ld(&bar[XB_TOPGEN]) == tg, bar);
;             __builtin_amdgcn_fence(__ATOMIC_ACQUIRE, "agent");
;             xb_add(&bar[XB_XGEN(x)], 1u);
;             asm volatile("s_waitcnt vmcnt(0)" ::: "memory");
;         } else {
;             XB_SPIN(xb_ld(&bar[XB_XGEN(x)]) == gen, bar);
;             __builtin_amdgcn_fence(__ATOMIC_ACQUIRE, "agent");
;             asm volatile("s_waitcnt vmcnt(0)" ::: "memory");
.LBB0_864:
	s_or_b64 exec, exec, s[8:9]
	v_cvt_f32_u32_e32 v4, v2
	s_waitcnt vmcnt(0)
	v_readfirstlane_b32 s2, v3
	v_sub_u32_e32 v3, 0, v2
	v_rcp_iflag_f32_e32 v4, v4
	v_add_u32_e32 v5, s2, v1
	v_mul_f32_e32 v4, 0x4f7ffffe, v4
	v_cvt_u32_f32_e32 v4, v4
	v_mul_lo_u32 v1, v3, v4
	v_mul_hi_u32 v1, v4, v1
	v_add_u32_e32 v1, v4, v1
	v_mul_hi_u32 v1, v5, v1
	v_mul_lo_u32 v3, v1, v2
	v_sub_u32_e32 v3, v5, v3
	v_add_u32_e32 v4, 1, v1
	v_cmp_ge_u32_e32 vcc, v3, v2
	s_nop 1
	v_cndmask_b32_e32 v1, v1, v4, vcc
	v_sub_u32_e32 v4, v3, v2
	v_cndmask_b32_e32 v3, v3, v4, vcc
	v_add_u32_e32 v4, 1, v1
	v_cmp_ge_u32_e32 vcc, v3, v2
	v_add_u32_e32 v3, 1, v5
	s_nop 0
	v_cndmask_b32_e32 v1, v1, v4, vcc
	v_mul_lo_u32 v4, v2, v1
	v_add_u32_e32 v2, v4, v2
	v_cmp_ne_u32_e32 vcc, v3, v2
	s_and_saveexec_b64 s[2:3], vcc
	s_xor_b64 s[6:7], exec, s[2:3]
	s_cbranch_execz .LBB0_878
	s_waitcnt lgkmcnt(0)
	buffer_inv sc1
	global_load_dword v0, v194, s[4:5] offset:1024 sc1
	s_add_u32 s10, s4, 0x2400
	s_addc_u32 s11, s5, 0
	s_waitcnt vmcnt(0)
	v_cmp_eq_u32_e32 vcc, v0, v1
	s_and_saveexec_b64 s[8:9], vcc
	s_cbranch_execz .LBB0_877
	s_mov_b32 s2, 0x40000
	global_load_dword v0, v33, s[10:11] sc1

; __device__ __forceinline__ unsigned xb_ld(unsigned* p)              { return __hip_atomic_load(p, __ATOMIC_RELAXED, __HIP_MEMORY_SCOPE_AGENT); }
; #define XB_SPIN(cond, bar) do { unsigned _sp = 0; while (cond) { __builtin_amdgcn_s_sleep(1); \
;     if ((++_sp & 255u) == 0u) { if (xb_ld(&(bar)[XB_TMO])) break; if (_sp > XB_SPIN_CAP) { atomicAdd(&(bar)[XB_TMO], 1u); break; } } } } while (0)
; __device__ __forceinline__ void xcd_barrier(unsigned* bar, unsigned x, volatile LAS unsigned* st) {
;     ...
;             XB_SPIN(xb_ld(&bar[XB_XGEN(x)]) == gen, bar);
;             __builtin_amdgcn_fence(__ATOMIC_ACQUIRE, "agent");
;             asm volatile("s_waitcnt vmcnt(0)" ::: "memory");
.LBB0_877:
	s_or_b64 exec, exec, s[8:9]
	s_waitcnt vmcnt(0)
	s_waitcnt vmcnt(0)

; __device__ __forceinline__ unsigned xb_ld(unsigned* p)              { return __hip_atomic_load(p, __ATOMIC_RELAXED, __HIP_MEMORY_SCOPE_AGENT); }
; __device__ __forceinline__ unsigned xb_add(unsigned* p, unsigned v) { return __hip_atomic_fetch_add(p, v, __ATOMIC_RELAXED, __HIP_MEMORY_SCOPE_AGENT); }
; #define XB_SPIN(cond, bar) do { unsigned _sp = 0; while (cond) { __builtin_amdgcn_s_sleep(1); \
;     if ((++_sp & 255u) == 0u) { if (xb_ld(&(bar)[XB_TMO])) break; if (_sp > XB_SPIN_CAP) { atomicAdd(&(bar)[XB_TMO], 1u); break; } } } } while (0)
; __device__ __forceinline__ void xcd_barrier(unsigned* bar, unsigned x, volatile LAS unsigned* st) {
;     ...
;             const unsigned og = xb_add(&bar[XB_TOP], 1u);
;             const unsigned tg = og / nx;
;             if (og + 1u == (tg + 1u) * nx) xb_add(&bar[XB_TOPGEN], 1u);
;             else XB_SPIN(xb_ld(&bar[XB_TOPGEN]) == tg, bar);
;             __builtin_amdgcn_fence(__ATOMIC_ACQUIRE, "agent");
.LBB0_881:
	s_or_b64 exec, exec, s[8:9]
	s_waitcnt vmcnt(0)
	buffer_inv sc1
	v_readfirstlane_b32 s2, v2
	v_cvt_f32_u32_e32 v2, v0
	v_sub_u32_e32 v3, 0, v0
	v_add_u32_e32 v1, s2, v1
	v_readlane_b32 s2, v254, 32
	v_rcp_iflag_f32_e32 v2, v2
	v_readlane_b32 s3, v254, 33
	s_mov_b64 s[8:9], -1
	v_mul_f32_e32 v2, 0x4f7ffffe, v2
	v_cvt_u32_f32_e32 v2, v2
	v_mul_lo_u32 v3, v3, v2
	v_mul_hi_u32 v3, v2, v3
	v_add_u32_e32 v2, v2, v3
	v_mul_hi_u32 v2, v1, v2
	v_mul_lo_u32 v3, v2, v0
	v_sub_u32_e32 v3, v1, v3
	v_cmp_ge_u32_e32 vcc, v3, v0
	v_add_u32_e32 v4, 1, v2
	v_add_u32_e32 v1, 1, v1
	v_cndmask_b32_e32 v2, v2, v4, vcc
	v_sub_u32_e32 v4, v3, v0
	v_cndmask_b32_e32 v3, v3, v4, vcc
	v_cmp_ge_u32_e32 vcc, v3, v0
	v_add_u32_e32 v3, 1, v2
	s_nop 0
	v_cndmask_b32_e32 v2, v2, v3, vcc
	v_mul_lo_u32 v3, v0, v2
	v_add_u32_e32 v0, v3, v0
	v_cmp_ne_u32_e32 vcc, v1, v0
	v_mov_b64_e32 v[0:1], s[2:3]
	s_and_saveexec_b64 s[6:7], vcc
	s_cbranch_execz .LBB0_893
	v_readlane_b32 s2, v254, 32
	v_readlane_b32 s3, v254, 33
	s_mov_b64 s[10:11], 0
	s_nop 3
	global_load_dword v0, v33, s[2:3] sc1
	s_waitcnt vmcnt(0)
	v_cmp_eq_u32_e32 vcc, v0, v2
	s_and_saveexec_b64 s[8:9], vcc
	s_cbranch_execz .LBB0_892
	s_mov_b32 s2, 1
	s_branch .LBB0_885
